# ffn_out tail K-loop: operand loads with sc1 (device scope, served from L2 without L1 allocation)
# baseline (speedup 1.0000x reference)
; #define TG_LOAD(A_, B_, KS_) do { const int ks_ = (KS_) < nks ? (KS_) : w; _Pragma("unroll") for (int i = 0; i < 4; ++i) { A_[i] = *(const bf16x8*)(ap + (size_t)i * 16 * K + ks_ * 32); B_[i] = *(const bf16x8*)(bp + (size_t)i * 16 * K + ks_ * 32); } } while (0)
; #define TG_MMA(A_, B_) do { _Pragma("unroll") for (int i = 0; i < 4; ++i) _Pragma("unroll") for (int j = 0; j < 4; ++j) acc[i][j] = __builtin_amdgcn_mfma_f32_16x16x32_bf16(A_[i], B_[j], acc[i][j], 0, 0, 0); } while (0)
; template <int EPI> __device__ __forceinline__ void tail_gemm(LAS unsigned char* lds, const bf16* Am, const bf16* Bt, int K, const TailEpi& E, int tid_in) {
;     ...
;     f32x4 acc[4][4];
; #pragma unroll
;     for (int i = 0; i < 4; ++i)
; #pragma unroll
;         for (int j = 0; j < 4; ++j) acc[i][j] = (f32x4){0.f, 0.f, 0.f, 0.f};
;     const bf16* ap = Am + (size_t)(row0 + l15) * K + q4 * 8;
;     const bf16* bp = Bt + (size_t)(col0 + l15) * K + q4 * 8;
;     {
;         const int nks = K / 32;
;         bf16x8 a0[4], b0[4], a1[4], b1[4], a2[4], b2[4];
;     ...
;         TG_LOAD(a0, b0, w); TG_LOAD(a1, b1, w + 8);
;         for (int ks = w; ks < nks; ks += 24) {
;             TG_LOAD(a2, b2, ks + 16); TG_MMA(a0, b0);
;             if (ks + 8 < nks) { TG_LOAD(a0, b0, ks + 24); TG_MMA(a1, b1); }
;             if (ks + 16 < nks) { TG_LOAD(a1, b1, ks + 32); TG_MMA(a2, b2); }
.LBB0_1753:
	s_lshl_b32 s0, s12, 2
	v_mov_b32_e32 v80, v81
	s_and_b32 s1, s0, 0xffffffc0
	s_and_b32 s13, s12, 15
	v_mov_b32_e32 v82, v81
	v_mov_b32_e32 v83, v81
	v_mov_b64_e32 v[4:5], v[80:81]
	s_waitcnt lgkmcnt(0)
	v_mov_b64_e32 v[0:1], v[80:81]
	v_mov_b64_e32 v[20:21], v[80:81]
	v_mov_b64_e32 v[16:17], v[80:81]
	v_mov_b64_e32 v[36:37], v[80:81]
	v_mov_b64_e32 v[32:33], v[80:81]
	v_mov_b64_e32 v[52:53], v[80:81]
	v_mov_b64_e32 v[48:49], v[80:81]
	v_mov_b64_e32 v[60:61], v[80:81]
	v_mov_b64_e32 v[56:57], v[80:81]
	s_waitcnt vmcnt(0)
	v_mov_b64_e32 v[44:45], v[80:81]
	v_mov_b64_e32 v[40:41], v[80:81]
	v_mov_b64_e32 v[28:29], v[80:81]
	v_mov_b64_e32 v[24:25], v[80:81]
	v_mov_b64_e32 v[12:13], v[80:81]
	v_mov_b64_e32 v[8:9], v[80:81]
	s_addk_i32 s1, 0x4000
	s_lshl_b32 s0, s13, 6
	v_mov_b64_e32 v[6:7], v[82:83]
	v_mov_b64_e32 v[2:3], v[82:83]
	v_mov_b64_e32 v[22:23], v[82:83]
	v_mov_b64_e32 v[18:19], v[82:83]
	v_mov_b64_e32 v[38:39], v[82:83]
	v_mov_b64_e32 v[34:35], v[82:83]
	v_mov_b64_e32 v[54:55], v[82:83]
	v_mov_b64_e32 v[50:51], v[82:83]
	v_mov_b64_e32 v[62:63], v[82:83]
	v_mov_b64_e32 v[58:59], v[82:83]
	v_mov_b64_e32 v[46:47], v[82:83]
	v_mov_b64_e32 v[42:43], v[82:83]
	v_mov_b64_e32 v[30:31], v[82:83]
	v_mov_b64_e32 v[26:27], v[82:83]
	v_mov_b64_e32 v[14:15], v[82:83]
	v_mov_b64_e32 v[10:11], v[82:83]
	s_and_saveexec_b64 s[2:3], s[36:37]
	s_cbranch_execz .LBB0_1761
	v_or_b32_e32 v0, s1, v177
	v_mad_i64_i32 v[172:173], s[4:5], v0, s92, v[164:165]
	v_or_b32_e32 v0, s0, v177
	v_mul_u32_u24_e32 v0, 0xb00, v0
	v_lshlrev_b32_e32 v80, 1, v0
	v_lshl_add_u64 v[174:175], v[166:167], 0, v[80:81]
	v_lshlrev_b32_e32 v80, 6, v176
	v_lshl_add_u64 v[172:173], v[172:173], 0, v[80:81]
	v_lshl_add_u64 v[174:175], v[174:175], 0, v[80:81]
	s_mov_b64 s[40:41], 0x16000
	v_mov_b32_e32 v80, v225
	v_lshl_add_u64 v[186:187], v[172:173], 0, s[40:41]
	v_lshl_add_u64 v[188:189], v[174:175], 0, s[40:41]
	v_lshl_add_u64 v[202:203], v[186:187], 0, s[40:41]
	v_lshl_add_u64 v[228:229], v[188:189], 0, s[40:41]
	v_lshl_add_u64 v[234:235], v[202:203], 0, s[40:41]
	v_lshl_add_u64 v[82:83], v[228:229], 0, s[40:41]
	global_load_dwordx4 v[64:67], v[172:173], off sc1
	global_load_dwordx4 v[68:71], v[174:175], off sc1
	global_load_dwordx4 v[72:75], v[186:187], off sc1
	global_load_dwordx4 v[76:79], v[188:189], off sc1
	global_load_dwordx4 v[84:87], v[202:203], off sc1
	global_load_dwordx4 v[88:91], v[228:229], off sc1
	global_load_dwordx4 v[92:95], v[234:235], off sc1
	global_load_dwordx4 v[96:99], v[82:83], off sc1
	global_load_dwordx4 v[100:103], v[172:173], off offset:512 sc1
	global_load_dwordx4 v[104:107], v[174:175], off offset:512 sc1
	global_load_dwordx4 v[108:111], v[186:187], off offset:512 sc1
	global_load_dwordx4 v[112:115], v[188:189], off offset:512 sc1
	global_load_dwordx4 v[116:119], v[202:203], off offset:512 sc1
	global_load_dwordx4 v[120:123], v[228:229], off offset:512 sc1
	global_load_dwordx4 v[124:127], v[234:235], off offset:512 sc1
	global_load_dwordx4 v[128:131], v[82:83], off offset:512 sc1
	global_load_dwordx4 v[132:135], v[172:173], off offset:1024 sc1
	global_load_dwordx4 v[136:139], v[174:175], off offset:1024 sc1
	global_load_dwordx4 v[140:143], v[186:187], off offset:1024 sc1
	global_load_dwordx4 v[144:147], v[188:189], off offset:1024 sc1
	global_load_dwordx4 v[148:151], v[202:203], off offset:1024 sc1
	global_load_dwordx4 v[152:155], v[228:229], off offset:1024 sc1
	global_load_dwordx4 v[156:159], v[234:235], off offset:1024 sc1
	global_load_dwordx4 v[160:163], v[82:83], off offset:1024 sc1
	global_load_dwordx4 v[204:207], v[172:173], off offset:1536 sc1
	global_load_dwordx4 v[208:211], v[174:175], off offset:1536 sc1
	global_load_dwordx4 v[212:215], v[186:187], off offset:1536 sc1
	global_load_dwordx4 v[224:227], v[188:189], off offset:1536 sc1
	global_load_dwordx4 v[236:239], v[202:203], off offset:1536 sc1
	global_load_dwordx4 v[240:243], v[228:229], off offset:1536 sc1
	global_load_dwordx4 v[244:247], v[234:235], off offset:1536 sc1
	global_load_dwordx4 v[248:251], v[82:83], off offset:1536 sc1
	s_waitcnt vmcnt(24)
	v_mfma_f32_16x16x32_bf16 v[60:63], v[64:67], v[68:71], v[60:63]
	v_mfma_f32_16x16x32_bf16 v[56:59], v[64:67], v[76:79], v[56:59]
	v_mfma_f32_16x16x32_bf16 v[44:47], v[64:67], v[88:91], v[44:47]
	v_mfma_f32_16x16x32_bf16 v[40:43], v[64:67], v[96:99], v[40:43]
	v_mfma_f32_16x16x32_bf16 v[28:31], v[72:75], v[68:71], v[28:31]
	v_mfma_f32_16x16x32_bf16 v[24:27], v[72:75], v[76:79], v[24:27]
	v_mfma_f32_16x16x32_bf16 v[12:15], v[72:75], v[88:91], v[12:15]
	v_mfma_f32_16x16x32_bf16 v[8:11], v[72:75], v[96:99], v[8:11]
	v_mfma_f32_16x16x32_bf16 v[48:51], v[84:87], v[68:71], v[48:51]
	v_mfma_f32_16x16x32_bf16 v[52:55], v[84:87], v[76:79], v[52:55]
	v_mfma_f32_16x16x32_bf16 v[32:35], v[84:87], v[88:91], v[32:35]
	v_mfma_f32_16x16x32_bf16 v[36:39], v[84:87], v[96:99], v[36:39]
	v_mfma_f32_16x16x32_bf16 v[16:19], v[92:95], v[68:71], v[16:19]
	v_mfma_f32_16x16x32_bf16 v[20:23], v[92:95], v[76:79], v[20:23]
	v_mfma_f32_16x16x32_bf16 v[0:3], v[92:95], v[88:91], v[0:3]
	v_mfma_f32_16x16x32_bf16 v[4:7], v[92:95], v[96:99], v[4:7]
	global_load_dwordx4 v[64:67], v[172:173], off offset:2048 sc1
	global_load_dwordx4 v[68:71], v[174:175], off offset:2048 sc1
	global_load_dwordx4 v[72:75], v[186:187], off offset:2048 sc1
	global_load_dwordx4 v[76:79], v[188:189], off offset:2048 sc1
	global_load_dwordx4 v[84:87], v[202:203], off offset:2048 sc1
	global_load_dwordx4 v[88:91], v[228:229], off offset:2048 sc1
	global_load_dwordx4 v[92:95], v[234:235], off offset:2048 sc1
	global_load_dwordx4 v[96:99], v[82:83], off offset:2048 sc1
	s_waitcnt vmcnt(24)
; #define TG_LOAD(A_, B_, KS_) do { const int ks_ = (KS_) < nks ? (KS_) : w; _Pragma("unroll") for (int i = 0; i < 4; ++i) { A_[i] = *(const bf16x8*)(ap + (size_t)i * 16 * K + ks_ * 32); B_[i] = *(const bf16x8*)(bp + (size_t)i * 16 * K + ks_ * 32); } } while (0)
; #define TG_MMA(A_, B_) do { _Pragma("unroll") for (int i = 0; i < 4; ++i) _Pragma("unroll") for (int j = 0; j < 4; ++j) acc[i][j] = __builtin_amdgcn_mfma_f32_16x16x32_bf16(A_[i], B_[j], acc[i][j], 0, 0, 0); } while (0)
; template <int EPI> __device__ __forceinline__ void tail_gemm(LAS unsigned char* lds, const bf16* Am, const bf16* Bt, int K, const TailEpi& E, int tid_in) {
;     ...
;         TG_LOAD(a0, b0, w); TG_LOAD(a1, b1, w + 8);
;         for (int ks = w; ks < nks; ks += 24) {
;             TG_LOAD(a2, b2, ks + 16); TG_MMA(a0, b0);
;             if (ks + 8 < nks) { TG_LOAD(a0, b0, ks + 24); TG_MMA(a1, b1); }
;             if (ks + 16 < nks) { TG_LOAD(a1, b1, ks + 32); TG_MMA(a2, b2); }
	v_mfma_f32_16x16x32_bf16 v[60:63], v[100:103], v[104:107], v[60:63]
	v_mfma_f32_16x16x32_bf16 v[56:59], v[100:103], v[112:115], v[56:59]
	v_mfma_f32_16x16x32_bf16 v[44:47], v[100:103], v[120:123], v[44:47]
	v_mfma_f32_16x16x32_bf16 v[40:43], v[100:103], v[128:131], v[40:43]
	v_mfma_f32_16x16x32_bf16 v[28:31], v[108:111], v[104:107], v[28:31]
	v_mfma_f32_16x16x32_bf16 v[24:27], v[108:111], v[112:115], v[24:27]
	v_mfma_f32_16x16x32_bf16 v[12:15], v[108:111], v[120:123], v[12:15]
	v_mfma_f32_16x16x32_bf16 v[8:11], v[108:111], v[128:131], v[8:11]
	v_mfma_f32_16x16x32_bf16 v[48:51], v[116:119], v[104:107], v[48:51]
	v_mfma_f32_16x16x32_bf16 v[52:55], v[116:119], v[112:115], v[52:55]
	v_mfma_f32_16x16x32_bf16 v[32:35], v[116:119], v[120:123], v[32:35]
	v_mfma_f32_16x16x32_bf16 v[36:39], v[116:119], v[128:131], v[36:39]
	v_mfma_f32_16x16x32_bf16 v[16:19], v[124:127], v[104:107], v[16:19]
	v_mfma_f32_16x16x32_bf16 v[20:23], v[124:127], v[112:115], v[20:23]
	v_mfma_f32_16x16x32_bf16 v[0:3], v[124:127], v[120:123], v[0:3]
	v_mfma_f32_16x16x32_bf16 v[4:7], v[124:127], v[128:131], v[4:7]
	global_load_dwordx4 v[100:103], v[172:173], off offset:2560 sc1
	global_load_dwordx4 v[104:107], v[174:175], off offset:2560 sc1
	global_load_dwordx4 v[108:111], v[186:187], off offset:2560 sc1
	global_load_dwordx4 v[112:115], v[188:189], off offset:2560 sc1
	global_load_dwordx4 v[116:119], v[202:203], off offset:2560 sc1
	global_load_dwordx4 v[120:123], v[228:229], off offset:2560 sc1
	global_load_dwordx4 v[124:127], v[234:235], off offset:2560 sc1
	global_load_dwordx4 v[128:131], v[82:83], off offset:2560 sc1
	s_waitcnt vmcnt(24)
	v_mfma_f32_16x16x32_bf16 v[60:63], v[132:135], v[136:139], v[60:63]
	v_mfma_f32_16x16x32_bf16 v[56:59], v[132:135], v[144:147], v[56:59]
	v_mfma_f32_16x16x32_bf16 v[44:47], v[132:135], v[152:155], v[44:47]
	v_mfma_f32_16x16x32_bf16 v[40:43], v[132:135], v[160:163], v[40:43]
	v_mfma_f32_16x16x32_bf16 v[28:31], v[140:143], v[136:139], v[28:31]
	v_mfma_f32_16x16x32_bf16 v[24:27], v[140:143], v[144:147], v[24:27]
	v_mfma_f32_16x16x32_bf16 v[12:15], v[140:143], v[152:155], v[12:15]
	v_mfma_f32_16x16x32_bf16 v[8:11], v[140:143], v[160:163], v[8:11]
	v_mfma_f32_16x16x32_bf16 v[48:51], v[148:151], v[136:139], v[48:51]
	v_mfma_f32_16x16x32_bf16 v[52:55], v[148:151], v[144:147], v[52:55]
	v_mfma_f32_16x16x32_bf16 v[32:35], v[148:151], v[152:155], v[32:35]
	v_mfma_f32_16x16x32_bf16 v[36:39], v[148:151], v[160:163], v[36:39]
	v_mfma_f32_16x16x32_bf16 v[16:19], v[156:159], v[136:139], v[16:19]
	v_mfma_f32_16x16x32_bf16 v[20:23], v[156:159], v[144:147], v[20:23]
	v_mfma_f32_16x16x32_bf16 v[0:3], v[156:159], v[152:155], v[0:3]
	v_mfma_f32_16x16x32_bf16 v[4:7], v[156:159], v[160:163], v[4:7]
	global_load_dwordx4 v[132:135], v[172:173], off offset:3072 sc1
	global_load_dwordx4 v[136:139], v[174:175], off offset:3072 sc1
	global_load_dwordx4 v[140:143], v[186:187], off offset:3072 sc1
	global_load_dwordx4 v[144:147], v[188:189], off offset:3072 sc1
	global_load_dwordx4 v[148:151], v[202:203], off offset:3072 sc1
	global_load_dwordx4 v[152:155], v[228:229], off offset:3072 sc1
	global_load_dwordx4 v[156:159], v[234:235], off offset:3072 sc1
	global_load_dwordx4 v[160:163], v[82:83], off offset:3072 sc1
	s_waitcnt vmcnt(24)
	v_mfma_f32_16x16x32_bf16 v[60:63], v[204:207], v[208:211], v[60:63]
	v_mfma_f32_16x16x32_bf16 v[56:59], v[204:207], v[224:227], v[56:59]
	v_mfma_f32_16x16x32_bf16 v[44:47], v[204:207], v[240:243], v[44:47]
	v_mfma_f32_16x16x32_bf16 v[40:43], v[204:207], v[248:251], v[40:43]
	v_mfma_f32_16x16x32_bf16 v[28:31], v[212:215], v[208:211], v[28:31]
	v_mfma_f32_16x16x32_bf16 v[24:27], v[212:215], v[224:227], v[24:27]
	v_mfma_f32_16x16x32_bf16 v[12:15], v[212:215], v[240:243], v[12:15]
	v_mfma_f32_16x16x32_bf16 v[8:11], v[212:215], v[248:251], v[8:11]
	v_mfma_f32_16x16x32_bf16 v[48:51], v[236:239], v[208:211], v[48:51]
	v_mfma_f32_16x16x32_bf16 v[52:55], v[236:239], v[224:227], v[52:55]
	v_mfma_f32_16x16x32_bf16 v[32:35], v[236:239], v[240:243], v[32:35]
	v_mfma_f32_16x16x32_bf16 v[36:39], v[236:239], v[248:251], v[36:39]
	v_mfma_f32_16x16x32_bf16 v[16:19], v[244:247], v[208:211], v[16:19]
	v_mfma_f32_16x16x32_bf16 v[20:23], v[244:247], v[224:227], v[20:23]
	v_mfma_f32_16x16x32_bf16 v[0:3], v[244:247], v[240:243], v[0:3]
	v_mfma_f32_16x16x32_bf16 v[4:7], v[244:247], v[248:251], v[4:7]
	global_load_dwordx4 v[204:207], v[172:173], off offset:3584 sc1
	global_load_dwordx4 v[208:211], v[174:175], off offset:3584 sc1
	global_load_dwordx4 v[212:215], v[186:187], off offset:3584 sc1
	global_load_dwordx4 v[224:227], v[188:189], off offset:3584 sc1
	global_load_dwordx4 v[236:239], v[202:203], off offset:3584 sc1
	global_load_dwordx4 v[240:243], v[228:229], off offset:3584 sc1
	global_load_dwordx4 v[244:247], v[234:235], off offset:3584 sc1
	global_load_dwordx4 v[248:251], v[82:83], off offset:3584 sc1
	s_waitcnt vmcnt(24)
; #define TG_LOAD(A_, B_, KS_) do { const int ks_ = (KS_) < nks ? (KS_) : w; _Pragma("unroll") for (int i = 0; i < 4; ++i) { A_[i] = *(const bf16x8*)(ap + (size_t)i * 16 * K + ks_ * 32); B_[i] = *(const bf16x8*)(bp + (size_t)i * 16 * K + ks_ * 32); } } while (0)
; #define TG_MMA(A_, B_) do { _Pragma("unroll") for (int i = 0; i < 4; ++i) _Pragma("unroll") for (int j = 0; j < 4; ++j) acc[i][j] = __builtin_amdgcn_mfma_f32_16x16x32_bf16(A_[i], B_[j], acc[i][j], 0, 0, 0); } while (0)
; template <int EPI> __device__ __forceinline__ void tail_gemm(LAS unsigned char* lds, const bf16* Am, const bf16* Bt, int K, const TailEpi& E, int tid_in) {
;     ...
;         TG_LOAD(a0, b0, w); TG_LOAD(a1, b1, w + 8);
;         for (int ks = w; ks < nks; ks += 24) {
;             TG_LOAD(a2, b2, ks + 16); TG_MMA(a0, b0);
;             if (ks + 8 < nks) { TG_LOAD(a0, b0, ks + 24); TG_MMA(a1, b1); }
;             if (ks + 16 < nks) { TG_LOAD(a1, b1, ks + 32); TG_MMA(a2, b2); }
	v_mfma_f32_16x16x32_bf16 v[60:63], v[64:67], v[68:71], v[60:63]
	v_mfma_f32_16x16x32_bf16 v[56:59], v[64:67], v[76:79], v[56:59]
	v_mfma_f32_16x16x32_bf16 v[44:47], v[64:67], v[88:91], v[44:47]
	v_mfma_f32_16x16x32_bf16 v[40:43], v[64:67], v[96:99], v[40:43]
	v_mfma_f32_16x16x32_bf16 v[28:31], v[72:75], v[68:71], v[28:31]
	v_mfma_f32_16x16x32_bf16 v[24:27], v[72:75], v[76:79], v[24:27]
	v_mfma_f32_16x16x32_bf16 v[12:15], v[72:75], v[88:91], v[12:15]
	v_mfma_f32_16x16x32_bf16 v[8:11], v[72:75], v[96:99], v[8:11]
	v_mfma_f32_16x16x32_bf16 v[48:51], v[84:87], v[68:71], v[48:51]
	v_mfma_f32_16x16x32_bf16 v[52:55], v[84:87], v[76:79], v[52:55]
	v_mfma_f32_16x16x32_bf16 v[32:35], v[84:87], v[88:91], v[32:35]
	v_mfma_f32_16x16x32_bf16 v[36:39], v[84:87], v[96:99], v[36:39]
	v_mfma_f32_16x16x32_bf16 v[16:19], v[92:95], v[68:71], v[16:19]
	v_mfma_f32_16x16x32_bf16 v[20:23], v[92:95], v[76:79], v[20:23]
	v_mfma_f32_16x16x32_bf16 v[0:3], v[92:95], v[88:91], v[0:3]
	v_mfma_f32_16x16x32_bf16 v[4:7], v[92:95], v[96:99], v[4:7]
	s_mov_b64 s[40:41], 0x1000
	v_lshl_add_u64 v[172:173], v[172:173], 0, s[40:41]
	v_lshl_add_u64 v[174:175], v[174:175], 0, s[40:41]
	v_lshl_add_u64 v[186:187], v[186:187], 0, s[40:41]
	v_lshl_add_u64 v[188:189], v[188:189], 0, s[40:41]
	v_lshl_add_u64 v[202:203], v[202:203], 0, s[40:41]
	v_lshl_add_u64 v[228:229], v[228:229], 0, s[40:41]
	v_lshl_add_u64 v[234:235], v[234:235], 0, s[40:41]
	v_lshl_add_u64 v[82:83], v[82:83], 0, s[40:41]
	global_load_dwordx4 v[64:67], v[172:173], off sc1
	global_load_dwordx4 v[68:71], v[174:175], off sc1
	global_load_dwordx4 v[72:75], v[186:187], off sc1
	global_load_dwordx4 v[76:79], v[188:189], off sc1
	global_load_dwordx4 v[84:87], v[202:203], off sc1
	global_load_dwordx4 v[88:91], v[228:229], off sc1
	global_load_dwordx4 v[92:95], v[234:235], off sc1
	global_load_dwordx4 v[96:99], v[82:83], off sc1
	s_waitcnt vmcnt(24)
	v_mfma_f32_16x16x32_bf16 v[60:63], v[100:103], v[104:107], v[60:63]
	v_mfma_f32_16x16x32_bf16 v[56:59], v[100:103], v[112:115], v[56:59]
	v_mfma_f32_16x16x32_bf16 v[44:47], v[100:103], v[120:123], v[44:47]
	v_mfma_f32_16x16x32_bf16 v[40:43], v[100:103], v[128:131], v[40:43]
	v_mfma_f32_16x16x32_bf16 v[28:31], v[108:111], v[104:107], v[28:31]
	v_mfma_f32_16x16x32_bf16 v[24:27], v[108:111], v[112:115], v[24:27]
	v_mfma_f32_16x16x32_bf16 v[12:15], v[108:111], v[120:123], v[12:15]
	v_mfma_f32_16x16x32_bf16 v[8:11], v[108:111], v[128:131], v[8:11]
	v_mfma_f32_16x16x32_bf16 v[48:51], v[116:119], v[104:107], v[48:51]
	v_mfma_f32_16x16x32_bf16 v[52:55], v[116:119], v[112:115], v[52:55]
	v_mfma_f32_16x16x32_bf16 v[32:35], v[116:119], v[120:123], v[32:35]
	v_mfma_f32_16x16x32_bf16 v[36:39], v[116:119], v[128:131], v[36:39]
	v_mfma_f32_16x16x32_bf16 v[16:19], v[124:127], v[104:107], v[16:19]
	v_mfma_f32_16x16x32_bf16 v[20:23], v[124:127], v[112:115], v[20:23]
	v_mfma_f32_16x16x32_bf16 v[0:3], v[124:127], v[120:123], v[0:3]
	v_mfma_f32_16x16x32_bf16 v[4:7], v[124:127], v[128:131], v[4:7]
	global_load_dwordx4 v[100:103], v[172:173], off offset:512 sc1
	global_load_dwordx4 v[104:107], v[174:175], off offset:512 sc1
	global_load_dwordx4 v[108:111], v[186:187], off offset:512 sc1
	global_load_dwordx4 v[112:115], v[188:189], off offset:512 sc1
	global_load_dwordx4 v[116:119], v[202:203], off offset:512 sc1
	global_load_dwordx4 v[120:123], v[228:229], off offset:512 sc1
	global_load_dwordx4 v[124:127], v[234:235], off offset:512 sc1
	global_load_dwordx4 v[128:131], v[82:83], off offset:512 sc1
	s_waitcnt vmcnt(24)
	v_mfma_f32_16x16x32_bf16 v[60:63], v[132:135], v[136:139], v[60:63]
	v_mfma_f32_16x16x32_bf16 v[56:59], v[132:135], v[144:147], v[56:59]
	v_mfma_f32_16x16x32_bf16 v[44:47], v[132:135], v[152:155], v[44:47]
	v_mfma_f32_16x16x32_bf16 v[40:43], v[132:135], v[160:163], v[40:43]
	v_mfma_f32_16x16x32_bf16 v[28:31], v[140:143], v[136:139], v[28:31]
	v_mfma_f32_16x16x32_bf16 v[24:27], v[140:143], v[144:147], v[24:27]
	v_mfma_f32_16x16x32_bf16 v[12:15], v[140:143], v[152:155], v[12:15]
	v_mfma_f32_16x16x32_bf16 v[8:11], v[140:143], v[160:163], v[8:11]
	v_mfma_f32_16x16x32_bf16 v[48:51], v[148:151], v[136:139], v[48:51]
	v_mfma_f32_16x16x32_bf16 v[52:55], v[148:151], v[144:147], v[52:55]
	v_mfma_f32_16x16x32_bf16 v[32:35], v[148:151], v[152:155], v[32:35]
	v_mfma_f32_16x16x32_bf16 v[36:39], v[148:151], v[160:163], v[36:39]
	v_mfma_f32_16x16x32_bf16 v[16:19], v[156:159], v[136:139], v[16:19]
	v_mfma_f32_16x16x32_bf16 v[20:23], v[156:159], v[144:147], v[20:23]
	v_mfma_f32_16x16x32_bf16 v[0:3], v[156:159], v[152:155], v[0:3]
	v_mfma_f32_16x16x32_bf16 v[4:7], v[156:159], v[160:163], v[4:7]
	global_load_dwordx4 v[132:135], v[172:173], off offset:1024 sc1
	global_load_dwordx4 v[136:139], v[174:175], off offset:1024 sc1
	global_load_dwordx4 v[140:143], v[186:187], off offset:1024 sc1
	global_load_dwordx4 v[144:147], v[188:189], off offset:1024 sc1
	global_load_dwordx4 v[148:151], v[202:203], off offset:1024 sc1
	global_load_dwordx4 v[152:155], v[228:229], off offset:1024 sc1
	global_load_dwordx4 v[156:159], v[234:235], off offset:1024 sc1
	global_load_dwordx4 v[160:163], v[82:83], off offset:1024 sc1
	s_waitcnt vmcnt(24)
; #define TG_LOAD(A_, B_, KS_) do { const int ks_ = (KS_) < nks ? (KS_) : w; _Pragma("unroll") for (int i = 0; i < 4; ++i) { A_[i] = *(const bf16x8*)(ap + (size_t)i * 16 * K + ks_ * 32); B_[i] = *(const bf16x8*)(bp + (size_t)i * 16 * K + ks_ * 32); } } while (0)
; #define TG_MMA(A_, B_) do { _Pragma("unroll") for (int i = 0; i < 4; ++i) _Pragma("unroll") for (int j = 0; j < 4; ++j) acc[i][j] = __builtin_amdgcn_mfma_f32_16x16x32_bf16(A_[i], B_[j], acc[i][j], 0, 0, 0); } while (0)
; template <int EPI> __device__ __forceinline__ void tail_gemm(LAS unsigned char* lds, const bf16* Am, const bf16* Bt, int K, const TailEpi& E, int tid_in) {
;     ...
;         TG_LOAD(a0, b0, w); TG_LOAD(a1, b1, w + 8);
;         for (int ks = w; ks < nks; ks += 24) {
;             TG_LOAD(a2, b2, ks + 16); TG_MMA(a0, b0);
;             if (ks + 8 < nks) { TG_LOAD(a0, b0, ks + 24); TG_MMA(a1, b1); }
;             if (ks + 16 < nks) { TG_LOAD(a1, b1, ks + 32); TG_MMA(a2, b2); }
;         }
	v_mfma_f32_16x16x32_bf16 v[60:63], v[204:207], v[208:211], v[60:63]
	v_mfma_f32_16x16x32_bf16 v[56:59], v[204:207], v[224:227], v[56:59]
	v_mfma_f32_16x16x32_bf16 v[44:47], v[204:207], v[240:243], v[44:47]
	v_mfma_f32_16x16x32_bf16 v[40:43], v[204:207], v[248:251], v[40:43]
	v_mfma_f32_16x16x32_bf16 v[28:31], v[212:215], v[208:211], v[28:31]
	v_mfma_f32_16x16x32_bf16 v[24:27], v[212:215], v[224:227], v[24:27]
	v_mfma_f32_16x16x32_bf16 v[12:15], v[212:215], v[240:243], v[12:15]
	v_mfma_f32_16x16x32_bf16 v[8:11], v[212:215], v[248:251], v[8:11]
	v_mfma_f32_16x16x32_bf16 v[48:51], v[236:239], v[208:211], v[48:51]
	v_mfma_f32_16x16x32_bf16 v[52:55], v[236:239], v[224:227], v[52:55]
	v_mfma_f32_16x16x32_bf16 v[32:35], v[236:239], v[240:243], v[32:35]
	v_mfma_f32_16x16x32_bf16 v[36:39], v[236:239], v[248:251], v[36:39]
	v_mfma_f32_16x16x32_bf16 v[16:19], v[244:247], v[208:211], v[16:19]
	v_mfma_f32_16x16x32_bf16 v[20:23], v[244:247], v[224:227], v[20:23]
	v_mfma_f32_16x16x32_bf16 v[0:3], v[244:247], v[240:243], v[0:3]
	v_mfma_f32_16x16x32_bf16 v[4:7], v[244:247], v[248:251], v[4:7]
	s_waitcnt vmcnt(16)
	v_mfma_f32_16x16x32_bf16 v[60:63], v[64:67], v[68:71], v[60:63]
	v_mfma_f32_16x16x32_bf16 v[56:59], v[64:67], v[76:79], v[56:59]
	v_mfma_f32_16x16x32_bf16 v[44:47], v[64:67], v[88:91], v[44:47]
	v_mfma_f32_16x16x32_bf16 v[40:43], v[64:67], v[96:99], v[40:43]
	v_mfma_f32_16x16x32_bf16 v[28:31], v[72:75], v[68:71], v[28:31]
	v_mfma_f32_16x16x32_bf16 v[24:27], v[72:75], v[76:79], v[24:27]
	v_mfma_f32_16x16x32_bf16 v[12:15], v[72:75], v[88:91], v[12:15]
	v_mfma_f32_16x16x32_bf16 v[8:11], v[72:75], v[96:99], v[8:11]
	v_mfma_f32_16x16x32_bf16 v[48:51], v[84:87], v[68:71], v[48:51]
	v_mfma_f32_16x16x32_bf16 v[52:55], v[84:87], v[76:79], v[52:55]
	v_mfma_f32_16x16x32_bf16 v[32:35], v[84:87], v[88:91], v[32:35]
	v_mfma_f32_16x16x32_bf16 v[36:39], v[84:87], v[96:99], v[36:39]
	v_mfma_f32_16x16x32_bf16 v[16:19], v[92:95], v[68:71], v[16:19]
	v_mfma_f32_16x16x32_bf16 v[20:23], v[92:95], v[76:79], v[20:23]
	v_mfma_f32_16x16x32_bf16 v[0:3], v[92:95], v[88:91], v[0:3]
	v_mfma_f32_16x16x32_bf16 v[4:7], v[92:95], v[96:99], v[4:7]
	s_waitcnt vmcnt(8)
	v_mfma_f32_16x16x32_bf16 v[60:63], v[100:103], v[104:107], v[60:63]
	v_mfma_f32_16x16x32_bf16 v[56:59], v[100:103], v[112:115], v[56:59]
	v_mfma_f32_16x16x32_bf16 v[44:47], v[100:103], v[120:123], v[44:47]
	v_mfma_f32_16x16x32_bf16 v[40:43], v[100:103], v[128:131], v[40:43]
	v_mfma_f32_16x16x32_bf16 v[28:31], v[108:111], v[104:107], v[28:31]
	v_mfma_f32_16x16x32_bf16 v[24:27], v[108:111], v[112:115], v[24:27]
	v_mfma_f32_16x16x32_bf16 v[12:15], v[108:111], v[120:123], v[12:15]
	v_mfma_f32_16x16x32_bf16 v[8:11], v[108:111], v[128:131], v[8:11]
	v_mfma_f32_16x16x32_bf16 v[48:51], v[116:119], v[104:107], v[48:51]
	v_mfma_f32_16x16x32_bf16 v[52:55], v[116:119], v[112:115], v[52:55]
	v_mfma_f32_16x16x32_bf16 v[32:35], v[116:119], v[120:123], v[32:35]
	v_mfma_f32_16x16x32_bf16 v[36:39], v[116:119], v[128:131], v[36:39]
	v_mfma_f32_16x16x32_bf16 v[16:19], v[124:127], v[104:107], v[16:19]
	v_mfma_f32_16x16x32_bf16 v[20:23], v[124:127], v[112:115], v[20:23]
	v_mfma_f32_16x16x32_bf16 v[0:3], v[124:127], v[120:123], v[0:3]
	v_mfma_f32_16x16x32_bf16 v[4:7], v[124:127], v[128:131], v[4:7]
	s_waitcnt vmcnt(0)
	v_mfma_f32_16x16x32_bf16 v[60:63], v[132:135], v[136:139], v[60:63]
	v_mfma_f32_16x16x32_bf16 v[56:59], v[132:135], v[144:147], v[56:59]
	v_mfma_f32_16x16x32_bf16 v[44:47], v[132:135], v[152:155], v[44:47]
	v_mfma_f32_16x16x32_bf16 v[40:43], v[132:135], v[160:163], v[40:43]
	v_mfma_f32_16x16x32_bf16 v[28:31], v[140:143], v[136:139], v[28:31]
	v_mfma_f32_16x16x32_bf16 v[24:27], v[140:143], v[144:147], v[24:27]
	v_mfma_f32_16x16x32_bf16 v[12:15], v[140:143], v[152:155], v[12:15]
	v_mfma_f32_16x16x32_bf16 v[8:11], v[140:143], v[160:163], v[8:11]
	v_mfma_f32_16x16x32_bf16 v[48:51], v[148:151], v[136:139], v[48:51]
	v_mfma_f32_16x16x32_bf16 v[52:55], v[148:151], v[144:147], v[52:55]
	v_mfma_f32_16x16x32_bf16 v[32:35], v[148:151], v[152:155], v[32:35]
	v_mfma_f32_16x16x32_bf16 v[36:39], v[148:151], v[160:163], v[36:39]
	v_mfma_f32_16x16x32_bf16 v[16:19], v[156:159], v[136:139], v[16:19]
	v_mfma_f32_16x16x32_bf16 v[20:23], v[156:159], v[144:147], v[20:23]
	v_mfma_f32_16x16x32_bf16 v[0:3], v[156:159], v[152:155], v[0:3]
	v_mfma_f32_16x16x32_bf16 v[4:7], v[156:159], v[160:163], v[4:7]
	v_mov_b32_e32 v225, v80
	v_mov_b32_e32 v82, v81
	v_mov_b32_e32 v83, v81
